# phase 8 (head norms + gates) prompt rows rewritten: 8/16-byte loads, sums inside DPP rows, next step's loads in flight
# speedup vs baseline: 1.1415x; 1.0099x over previous
.LBB0_1867:
	s_cmp_lt_i32 s4, 9
	s_cselect_b64 s[0:1], -1, 0
	s_cmp_gt_i32 s5, 8
	s_cselect_b64 s[2:3], -1, 0
	s_and_b64 s[0:1], s[0:1], s[2:3]
	s_andn2_b64 vcc, exec, s[0:1]
	s_cbranch_vccnz .LBB0_1983
	s_lshl_b32 s8, s28, 3
	s_cmp_lg_u32 s88, 0x100
	s_cbranch_scc1 .Lpost_orig
	v_and_b32_e32 v2, 63, v34
	v_lshrrev_b32_e32 v3, 6, v34
	v_and_b32_e32 v4, 31, v2
	v_lshlrev_b32_e32 v5, 7, v3
	v_lshl_add_u32 v6, v4, 2, v5
	v_and_b32_e32 v7, 15, v2
	v_lshl_add_u32 v8, v7, 3, v5
	v_lshrrev_b32_e32 v9, 5, v2
	v_lshrrev_b32_e32 v10, 4, v2
	v_lshrrev_b32_e32 v11, 4, v4
	v_lshl_add_u32 v11, v3, 1, v11
	v_lshlrev_b32_e32 v12, 1, v6
	v_lshlrev_b32_e32 v13, 1, v8
	v_lshl_add_u32 v68, v9, 11, v12
	v_mul_u32_u24_e32 v14, 0x5c00, v9
	v_add_u32_e32 v69, v14, v12
	v_add_u32_e32 v69, 0x1000, v69
	v_lshlrev_b32_e32 v14, 2, v11
	v_lshl_add_u32 v71, v9, 6, v14
	v_lshl_add_u32 v72, v9, 12, v12
	v_lshl_add_u32 v73, v10, 11, v13
	v_mul_u32_u24_e32 v14, 0x5c00, v10
	v_add_u32_e32 v74, v14, v13
	v_add_u32_e32 v74, 0x3400, v74
	v_lshl_add_u32 v75, v10, 12, v13
	v_add_u32_e32 v75, 0x800, v75
	v_readlane_b32 s12, v254, 29
	v_readlane_b32 s13, v254, 30
	v_readlane_b32 s14, v254, 31
	v_readlane_b32 s15, v254, 32
	v_readlane_b32 s16, v254, 33
	v_readlane_b32 s17, v254, 34
	v_readlane_b32 s18, v254, 35
	v_readlane_b32 s19, v254, 36
	v_lshlrev_b32_e32 v14, 2, v6
	v_lshlrev_b32_e32 v15, 2, v8
	s_nop 4
	global_load_dwordx4 v[40:43], v14, s[12:13]
	global_load_dwordx4 v[44:47], v14, s[14:15]
	global_load_dwordx4 v[52:55], v15, s[16:17]
	global_load_dwordx4 v[56:59], v15, s[16:17] offset:16
	global_load_dwordx4 v[60:63], v15, s[18:19]
	global_load_dwordx4 v[64:67], v15, s[18:19] offset:16
	v_add_u32_e32 v14, 0x2000, v14
	global_load_dwordx4 v[48:51], v14, s[58:59]
	s_lshl_b32 s0, s28, 14
	s_mul_i32 s1, s28, 0x2e000
	s_lshl_b32 s2, s28, 9
	s_lshl_b32 s3, s28, 15
	s_add_u32 s10, s34, 0x9122200
	s_addc_u32 s11, s35, 0
	s_add_u32 s10, s10, s0
	s_addc_u32 s11, s11, 0
	s_add_u32 s12, s34, 0x1d2e2200
	s_addc_u32 s13, s35, 0
	s_add_u32 s12, s12, s0
	s_addc_u32 s13, s13, 0
	s_add_u32 s14, s34, 0xd322200
	s_addc_u32 s15, s35, 0
	s_add_u32 s14, s14, s1
	s_addc_u32 s15, s15, 0
	s_sub_u32 s16, s14, 0x5c00
	s_subb_u32 s17, s15, 0
	s_add_u32 s18, s34, 0x8a70200
	s_addc_u32 s19, s35, 0
	s_add_u32 s18, s18, s2
	s_addc_u32 s19, s19, 0
	s_add_u32 s20, s34, 0xb222200
	s_addc_u32 s21, s35, 0
	s_add_u32 s20, s20, s3
	s_addc_u32 s21, s21, 0
	s_add_u32 s22, s82, s0
	s_addc_u32 s23, s83, 0
	s_mov_b64 s[24:25], s[14:15]
	s_mov_b64 s[26:27], s[20:21]
	s_cmp_eq_u32 s28, 0
	s_cselect_b32 s44, -1, 0
	s_mov_b32 s45, 0
	s_mov_b32 s30, 4
	global_load_dwordx2 v[80:81], v68, s[10:11] nt
	global_load_dwordx2 v[82:83], v69, s[14:15]
	global_load_dwordx2 v[84:85], v69, s[16:17]
	global_load_dword v88, v71, s[18:19]
	global_load_dwordx2 v[86:87], v68, s[12:13] nt
	s_add_u32 s10, s10, 0x1000
	s_addc_u32 s11, s11, 0
	s_add_u32 s12, s12, 0x1000
	s_addc_u32 s13, s13, 0
	s_add_u32 s14, s14, 0xb800
	s_addc_u32 s15, s15, 0
	s_add_u32 s16, s16, 0xb800
	s_addc_u32 s17, s17, 0
	s_add_u32 s18, s18, 0x80
	s_addc_u32 s19, s19, 0
	global_load_dwordx2 v[90:91], v68, s[10:11] nt
	global_load_dwordx2 v[92:93], v69, s[14:15]
	global_load_dwordx2 v[94:95], v69, s[16:17]
	global_load_dword v98, v71, s[18:19]
	global_load_dwordx2 v[96:97], v68, s[12:13] nt
	s_add_u32 s10, s10, 0x1000
	s_addc_u32 s11, s11, 0
	s_add_u32 s12, s12, 0x1000
	s_addc_u32 s13, s13, 0
	s_add_u32 s14, s14, 0xb800
	s_addc_u32 s15, s15, 0
	s_add_u32 s16, s16, 0xb800
	s_addc_u32 s17, s17, 0
	s_add_u32 s18, s18, 0x80
	s_addc_u32 s19, s19, 0
	global_load_dwordx2 v[100:101], v68, s[10:11] nt
	global_load_dwordx2 v[102:103], v69, s[14:15]
	global_load_dwordx2 v[104:105], v69, s[16:17]
	global_load_dword v108, v71, s[18:19]
	global_load_dwordx2 v[106:107], v68, s[12:13] nt
	s_add_u32 s10, s10, 0x1000
	s_addc_u32 s11, s11, 0
	s_add_u32 s12, s12, 0x1000
	s_addc_u32 s13, s13, 0
	s_add_u32 s14, s14, 0xb800
	s_addc_u32 s15, s15, 0
	s_add_u32 s16, s16, 0xb800
	s_addc_u32 s17, s17, 0
	s_add_u32 s18, s18, 0x80
	s_addc_u32 s19, s19, 0
	global_load_dwordx2 v[110:111], v68, s[10:11] nt
	global_load_dwordx2 v[112:113], v69, s[14:15]
	global_load_dwordx2 v[114:115], v69, s[16:17]
	global_load_dword v118, v71, s[18:19]
	global_load_dwordx2 v[116:117], v68, s[12:13] nt
	s_add_u32 s10, s10, 0x1000
	s_addc_u32 s11, s11, 0
	s_add_u32 s12, s12, 0x1000
	s_addc_u32 s13, s13, 0
	s_add_u32 s14, s14, 0xb800
	s_addc_u32 s15, s15, 0
	s_add_u32 s16, s16, 0xb800
	s_addc_u32 s17, s17, 0
	s_add_u32 s18, s18, 0x80
	s_addc_u32 s19, s19, 0
	global_load_dwordx4 v[120:123], v73, s[22:23] nt
	global_load_dwordx4 v[124:127], v74, s[24:25]
	s_add_u32 s22, s22, 0x2000
	s_addc_u32 s23, s23, 0
	s_add_u32 s24, s24, 0x17000
	s_addc_u32 s25, s25, 0
	global_load_dwordx4 v[128:131], v73, s[22:23] nt
	global_load_dwordx4 v[132:135], v74, s[24:25]
	s_add_u32 s22, s22, 0x2000
	s_addc_u32 s23, s23, 0
	s_add_u32 s24, s24, 0x17000
	s_addc_u32 s25, s25, 0
	s_add_u32 s10, s10, 0x3fc000
	s_addc_u32 s11, s11, 0
	s_add_u32 s12, s12, 0x3fc000
	s_addc_u32 s13, s13, 0
	s_add_u32 s14, s14, 0x2dd2000
	s_addc_u32 s15, s15, 0
	s_add_u32 s16, s16, 0x2dd2000
	s_addc_u32 s17, s17, 0
	s_add_u32 s18, s18, 0x1fe00
	s_addc_u32 s19, s19, 0
	s_add_u32 s22, s22, 0x3fc000
	s_addc_u32 s23, s23, 0
	s_add_u32 s24, s24, 0x2dd2000
	s_addc_u32 s25, s25, 0
.Lpost_step:
	s_waitcnt vmcnt(19)
	v_cndmask_b32_e64 v84, v84, 0, s[44:45]
	v_cndmask_b32_e64 v85, v85, 0, s[44:45]
	v_lshlrev_b32_e32 v2, 16, v80
	v_and_b32_e32 v3, 0xffff0000, v80
	v_lshlrev_b32_e32 v4, 16, v81
	v_and_b32_e32 v5, 0xffff0000, v81
	v_lshlrev_b32_e32 v6, 16, v82
	v_and_b32_e32 v7, 0xffff0000, v82
	v_lshlrev_b32_e32 v8, 16, v83
	v_and_b32_e32 v9, 0xffff0000, v83
	v_lshlrev_b32_e32 v10, 16, v84
	v_and_b32_e32 v11, 0xffff0000, v84
	v_lshlrev_b32_e32 v12, 16, v85
	v_and_b32_e32 v13, 0xffff0000, v85
	v_lshlrev_b32_e32 v14, 16, v86
	v_and_b32_e32 v15, 0xffff0000, v86
	v_lshlrev_b32_e32 v16, 16, v87
	v_and_b32_e32 v17, 0xffff0000, v87
	v_mov_b32_e32 v18, v88
	global_load_dwordx2 v[80:81], v68, s[10:11] nt
	global_load_dwordx2 v[82:83], v69, s[14:15]
	global_load_dwordx2 v[84:85], v69, s[16:17]
	global_load_dword v88, v71, s[18:19]
	global_load_dwordx2 v[86:87], v68, s[12:13] nt
	s_add_u32 s10, s10, 0x1000
	s_addc_u32 s11, s11, 0
	s_add_u32 s12, s12, 0x1000
	s_addc_u32 s13, s13, 0
	s_add_u32 s14, s14, 0xb800
	s_addc_u32 s15, s15, 0
	s_add_u32 s16, s16, 0xb800
	s_addc_u32 s17, s17, 0
	s_add_u32 s18, s18, 0x80
	s_addc_u32 s19, s19, 0
	v_add_f32_e32 v19, v2, v3
	v_add_f32_e32 v20, v4, v5
	v_sub_f32_e32 v10, v10, v6
	v_sub_f32_e32 v11, v11, v7
	v_add_f32_e32 v19, v19, v20
	v_sub_f32_e32 v12, v12, v8
	v_sub_f32_e32 v13, v13, v9
	s_nop 1
	v_add_f32_dpp v19, v19, v19 quad_perm:[1,0,3,2] row_mask:0xf bank_mask:0xf bound_ctrl:1
	s_nop 1
	v_add_f32_dpp v19, v19, v19 quad_perm:[2,3,0,1] row_mask:0xf bank_mask:0xf bound_ctrl:1
	s_nop 1
	v_add_f32_dpp v19, v19, v19 row_half_mirror row_mask:0xf bank_mask:0xf bound_ctrl:1
	s_nop 1
	v_add_f32_dpp v19, v19, v19 row_mirror row_mask:0xf bank_mask:0xf bound_ctrl:1
	v_fmac_f32_e32 v6, v48, v10
	v_fmac_f32_e32 v7, v49, v11
	v_fmac_f32_e32 v8, v50, v12
	v_fmac_f32_e32 v9, v51, v13
	v_mul_f32_e32 v19, 0x3c800000, v19
	v_sub_f32_e32 v2, v2, v19
	v_sub_f32_e32 v3, v3, v19
	v_sub_f32_e32 v4, v4, v19
	v_sub_f32_e32 v5, v5, v19
	v_mul_f32_e32 v20, v2, v2
	v_mul_f32_e32 v21, v3, v3
	v_fmac_f32_e32 v20, v4, v4
	v_fmac_f32_e32 v21, v5, v5
	v_mul_f32_e32 v6, v18, v6
	v_mul_f32_e32 v7, v18, v7
	v_mul_f32_e32 v8, v18, v8
	v_mul_f32_e32 v9, v18, v9
	v_add_f32_e32 v20, v20, v21
	v_add_f32_e32 v6, v44, v6
	v_add_f32_e32 v7, v45, v7
	v_add_f32_e32 v8, v46, v8
	v_add_f32_e32 v9, v47, v9
	s_nop 1
	v_add_f32_dpp v20, v20, v20 quad_perm:[1,0,3,2] row_mask:0xf bank_mask:0xf bound_ctrl:1
	s_nop 1
	v_add_f32_dpp v20, v20, v20 quad_perm:[2,3,0,1] row_mask:0xf bank_mask:0xf bound_ctrl:1
	s_nop 1
	v_add_f32_dpp v20, v20, v20 row_half_mirror row_mask:0xf bank_mask:0xf bound_ctrl:1
	s_nop 1
	v_add_f32_dpp v20, v20, v20 row_mirror row_mask:0xf bank_mask:0xf bound_ctrl:1
	v_mov_b32_e32 v21, 0x3a27c5ac
	v_fmac_f32_e32 v21, 0x3c800000, v20
	v_rsq_f32_e32 v21, v21
	s_nop 0
	v_mul_f32_e32 v2, v2, v21
	v_mul_f32_e32 v3, v3, v21
	v_mul_f32_e32 v4, v4, v21
	v_mul_f32_e32 v5, v5, v21
	v_fmac_f32_e32 v6, v2, v40
	v_fmac_f32_e32 v7, v3, v41
	v_fmac_f32_e32 v8, v4, v42
	v_fmac_f32_e32 v9, v5, v43
	v_mul_f32_e32 v6, v6, v14
	v_mul_f32_e32 v7, v7, v15
	v_mul_f32_e32 v8, v8, v16
	v_mul_f32_e32 v9, v9, v17
	v_cvt_pk_bf16_f32 v20, v6, v7
	v_cvt_pk_bf16_f32 v21, v8, v9
	global_store_dwordx2 v72, v[20:21], s[20:21]
	s_add_u32 s20, s20, 0x2000
	s_addc_u32 s21, s21, 0
	s_waitcnt vmcnt(20)
	v_lshlrev_b32_e32 v2, 16, v90
	v_and_b32_e32 v3, 0xffff0000, v90
	v_lshlrev_b32_e32 v4, 16, v91
	v_and_b32_e32 v5, 0xffff0000, v91
	v_lshlrev_b32_e32 v6, 16, v92
	v_and_b32_e32 v7, 0xffff0000, v92
	v_lshlrev_b32_e32 v8, 16, v93
	v_and_b32_e32 v9, 0xffff0000, v93
	v_lshlrev_b32_e32 v10, 16, v94
	v_and_b32_e32 v11, 0xffff0000, v94
	v_lshlrev_b32_e32 v12, 16, v95
	v_and_b32_e32 v13, 0xffff0000, v95
	v_lshlrev_b32_e32 v14, 16, v96
	v_and_b32_e32 v15, 0xffff0000, v96
	v_lshlrev_b32_e32 v16, 16, v97
	v_and_b32_e32 v17, 0xffff0000, v97
	v_mov_b32_e32 v18, v98
	global_load_dwordx2 v[90:91], v68, s[10:11] nt
	global_load_dwordx2 v[92:93], v69, s[14:15]
	global_load_dwordx2 v[94:95], v69, s[16:17]
	global_load_dword v98, v71, s[18:19]
	global_load_dwordx2 v[96:97], v68, s[12:13] nt
	s_add_u32 s10, s10, 0x1000
	s_addc_u32 s11, s11, 0
	s_add_u32 s12, s12, 0x1000
	s_addc_u32 s13, s13, 0
	s_add_u32 s14, s14, 0xb800
	s_addc_u32 s15, s15, 0
	s_add_u32 s16, s16, 0xb800
	s_addc_u32 s17, s17, 0
	s_add_u32 s18, s18, 0x80
	s_addc_u32 s19, s19, 0
	v_add_f32_e32 v19, v2, v3
	v_add_f32_e32 v20, v4, v5
	v_sub_f32_e32 v10, v10, v6
	v_sub_f32_e32 v11, v11, v7
	v_add_f32_e32 v19, v19, v20
	v_sub_f32_e32 v12, v12, v8
	v_sub_f32_e32 v13, v13, v9
	s_nop 1
	v_add_f32_dpp v19, v19, v19 quad_perm:[1,0,3,2] row_mask:0xf bank_mask:0xf bound_ctrl:1
	s_nop 1
	v_add_f32_dpp v19, v19, v19 quad_perm:[2,3,0,1] row_mask:0xf bank_mask:0xf bound_ctrl:1
	s_nop 1
	v_add_f32_dpp v19, v19, v19 row_half_mirror row_mask:0xf bank_mask:0xf bound_ctrl:1
	s_nop 1
	v_add_f32_dpp v19, v19, v19 row_mirror row_mask:0xf bank_mask:0xf bound_ctrl:1
	v_fmac_f32_e32 v6, v48, v10
	v_fmac_f32_e32 v7, v49, v11
	v_fmac_f32_e32 v8, v50, v12
	v_fmac_f32_e32 v9, v51, v13
	v_mul_f32_e32 v19, 0x3c800000, v19
	v_sub_f32_e32 v2, v2, v19
	v_sub_f32_e32 v3, v3, v19
	v_sub_f32_e32 v4, v4, v19
	v_sub_f32_e32 v5, v5, v19
	v_mul_f32_e32 v20, v2, v2
	v_mul_f32_e32 v21, v3, v3
	v_fmac_f32_e32 v20, v4, v4
	v_fmac_f32_e32 v21, v5, v5
	v_mul_f32_e32 v6, v18, v6
	v_mul_f32_e32 v7, v18, v7
	v_mul_f32_e32 v8, v18, v8
	v_mul_f32_e32 v9, v18, v9
	v_add_f32_e32 v20, v20, v21
	v_add_f32_e32 v6, v44, v6
	v_add_f32_e32 v7, v45, v7
	v_add_f32_e32 v8, v46, v8
	v_add_f32_e32 v9, v47, v9
	s_nop 1
	v_add_f32_dpp v20, v20, v20 quad_perm:[1,0,3,2] row_mask:0xf bank_mask:0xf bound_ctrl:1
	s_nop 1
	v_add_f32_dpp v20, v20, v20 quad_perm:[2,3,0,1] row_mask:0xf bank_mask:0xf bound_ctrl:1
	s_nop 1
	v_add_f32_dpp v20, v20, v20 row_half_mirror row_mask:0xf bank_mask:0xf bound_ctrl:1
	s_nop 1
	v_add_f32_dpp v20, v20, v20 row_mirror row_mask:0xf bank_mask:0xf bound_ctrl:1
	v_mov_b32_e32 v21, 0x3a27c5ac
	v_fmac_f32_e32 v21, 0x3c800000, v20
	v_rsq_f32_e32 v21, v21
	s_nop 0
	v_mul_f32_e32 v2, v2, v21
	v_mul_f32_e32 v3, v3, v21
	v_mul_f32_e32 v4, v4, v21
	v_mul_f32_e32 v5, v5, v21
	v_fmac_f32_e32 v6, v2, v40
	v_fmac_f32_e32 v7, v3, v41
	v_fmac_f32_e32 v8, v4, v42
	v_fmac_f32_e32 v9, v5, v43
	v_mul_f32_e32 v6, v6, v14
	v_mul_f32_e32 v7, v7, v15
	v_mul_f32_e32 v8, v8, v16
	v_mul_f32_e32 v9, v9, v17
	v_cvt_pk_bf16_f32 v20, v6, v7
	v_cvt_pk_bf16_f32 v21, v8, v9
	global_store_dwordx2 v72, v[20:21], s[20:21]
	s_add_u32 s20, s20, 0x2000
	s_addc_u32 s21, s21, 0
	s_waitcnt vmcnt(21)
	v_lshlrev_b32_e32 v2, 16, v100
	v_and_b32_e32 v3, 0xffff0000, v100
	v_lshlrev_b32_e32 v4, 16, v101
	v_and_b32_e32 v5, 0xffff0000, v101
	v_lshlrev_b32_e32 v6, 16, v102
	v_and_b32_e32 v7, 0xffff0000, v102
	v_lshlrev_b32_e32 v8, 16, v103
	v_and_b32_e32 v9, 0xffff0000, v103
	v_lshlrev_b32_e32 v10, 16, v104
	v_and_b32_e32 v11, 0xffff0000, v104
	v_lshlrev_b32_e32 v12, 16, v105
	v_and_b32_e32 v13, 0xffff0000, v105
	v_lshlrev_b32_e32 v14, 16, v106
	v_and_b32_e32 v15, 0xffff0000, v106
	v_lshlrev_b32_e32 v16, 16, v107
	v_and_b32_e32 v17, 0xffff0000, v107
	v_mov_b32_e32 v18, v108
	global_load_dwordx2 v[100:101], v68, s[10:11] nt
	global_load_dwordx2 v[102:103], v69, s[14:15]
	global_load_dwordx2 v[104:105], v69, s[16:17]
	global_load_dword v108, v71, s[18:19]
	global_load_dwordx2 v[106:107], v68, s[12:13] nt
	s_add_u32 s10, s10, 0x1000
	s_addc_u32 s11, s11, 0
	s_add_u32 s12, s12, 0x1000
	s_addc_u32 s13, s13, 0
	s_add_u32 s14, s14, 0xb800
	s_addc_u32 s15, s15, 0
	s_add_u32 s16, s16, 0xb800
	s_addc_u32 s17, s17, 0
	s_add_u32 s18, s18, 0x80
	s_addc_u32 s19, s19, 0
	v_add_f32_e32 v19, v2, v3
	v_add_f32_e32 v20, v4, v5
	v_sub_f32_e32 v10, v10, v6
	v_sub_f32_e32 v11, v11, v7
	v_add_f32_e32 v19, v19, v20
	v_sub_f32_e32 v12, v12, v8
	v_sub_f32_e32 v13, v13, v9
	s_nop 1
	v_add_f32_dpp v19, v19, v19 quad_perm:[1,0,3,2] row_mask:0xf bank_mask:0xf bound_ctrl:1
	s_nop 1
	v_add_f32_dpp v19, v19, v19 quad_perm:[2,3,0,1] row_mask:0xf bank_mask:0xf bound_ctrl:1
	s_nop 1
	v_add_f32_dpp v19, v19, v19 row_half_mirror row_mask:0xf bank_mask:0xf bound_ctrl:1
	s_nop 1
	v_add_f32_dpp v19, v19, v19 row_mirror row_mask:0xf bank_mask:0xf bound_ctrl:1
	v_fmac_f32_e32 v6, v48, v10
	v_fmac_f32_e32 v7, v49, v11
	v_fmac_f32_e32 v8, v50, v12
	v_fmac_f32_e32 v9, v51, v13
	v_mul_f32_e32 v19, 0x3c800000, v19
	v_sub_f32_e32 v2, v2, v19
	v_sub_f32_e32 v3, v3, v19
	v_sub_f32_e32 v4, v4, v19
	v_sub_f32_e32 v5, v5, v19
	v_mul_f32_e32 v20, v2, v2
	v_mul_f32_e32 v21, v3, v3
	v_fmac_f32_e32 v20, v4, v4
	v_fmac_f32_e32 v21, v5, v5
	v_mul_f32_e32 v6, v18, v6
	v_mul_f32_e32 v7, v18, v7
	v_mul_f32_e32 v8, v18, v8
	v_mul_f32_e32 v9, v18, v9
	v_add_f32_e32 v20, v20, v21
	v_add_f32_e32 v6, v44, v6
	v_add_f32_e32 v7, v45, v7
	v_add_f32_e32 v8, v46, v8
	v_add_f32_e32 v9, v47, v9
	s_nop 1
	v_add_f32_dpp v20, v20, v20 quad_perm:[1,0,3,2] row_mask:0xf bank_mask:0xf bound_ctrl:1
	s_nop 1
	v_add_f32_dpp v20, v20, v20 quad_perm:[2,3,0,1] row_mask:0xf bank_mask:0xf bound_ctrl:1
	s_nop 1
	v_add_f32_dpp v20, v20, v20 row_half_mirror row_mask:0xf bank_mask:0xf bound_ctrl:1
	s_nop 1
	v_add_f32_dpp v20, v20, v20 row_mirror row_mask:0xf bank_mask:0xf bound_ctrl:1
	v_mov_b32_e32 v21, 0x3a27c5ac
	v_fmac_f32_e32 v21, 0x3c800000, v20
	v_rsq_f32_e32 v21, v21
	s_nop 0
	v_mul_f32_e32 v2, v2, v21
	v_mul_f32_e32 v3, v3, v21
	v_mul_f32_e32 v4, v4, v21
	v_mul_f32_e32 v5, v5, v21
	v_fmac_f32_e32 v6, v2, v40
	v_fmac_f32_e32 v7, v3, v41
	v_fmac_f32_e32 v8, v4, v42
	v_fmac_f32_e32 v9, v5, v43
	v_mul_f32_e32 v6, v6, v14
	v_mul_f32_e32 v7, v7, v15
	v_mul_f32_e32 v8, v8, v16
	v_mul_f32_e32 v9, v9, v17
	v_cvt_pk_bf16_f32 v20, v6, v7
	v_cvt_pk_bf16_f32 v21, v8, v9
	global_store_dwordx2 v72, v[20:21], s[20:21]
	s_add_u32 s20, s20, 0x2000
	s_addc_u32 s21, s21, 0
	s_waitcnt vmcnt(22)
	v_lshlrev_b32_e32 v2, 16, v110
	v_and_b32_e32 v3, 0xffff0000, v110
	v_lshlrev_b32_e32 v4, 16, v111
	v_and_b32_e32 v5, 0xffff0000, v111
	v_lshlrev_b32_e32 v6, 16, v112
	v_and_b32_e32 v7, 0xffff0000, v112
	v_lshlrev_b32_e32 v8, 16, v113
	v_and_b32_e32 v9, 0xffff0000, v113
	v_lshlrev_b32_e32 v10, 16, v114
	v_and_b32_e32 v11, 0xffff0000, v114
	v_lshlrev_b32_e32 v12, 16, v115
	v_and_b32_e32 v13, 0xffff0000, v115
	v_lshlrev_b32_e32 v14, 16, v116
	v_and_b32_e32 v15, 0xffff0000, v116
	v_lshlrev_b32_e32 v16, 16, v117
	v_and_b32_e32 v17, 0xffff0000, v117
	v_mov_b32_e32 v18, v118
	global_load_dwordx2 v[110:111], v68, s[10:11] nt
	global_load_dwordx2 v[112:113], v69, s[14:15]
	global_load_dwordx2 v[114:115], v69, s[16:17]
	global_load_dword v118, v71, s[18:19]
	global_load_dwordx2 v[116:117], v68, s[12:13] nt
	s_add_u32 s10, s10, 0x1000
	s_addc_u32 s11, s11, 0
	s_add_u32 s12, s12, 0x1000
	s_addc_u32 s13, s13, 0
	s_add_u32 s14, s14, 0xb800
	s_addc_u32 s15, s15, 0
	s_add_u32 s16, s16, 0xb800
	s_addc_u32 s17, s17, 0
	s_add_u32 s18, s18, 0x80
	s_addc_u32 s19, s19, 0
	v_add_f32_e32 v19, v2, v3
	v_add_f32_e32 v20, v4, v5
	v_sub_f32_e32 v10, v10, v6
	v_sub_f32_e32 v11, v11, v7
	v_add_f32_e32 v19, v19, v20
	v_sub_f32_e32 v12, v12, v8
	v_sub_f32_e32 v13, v13, v9
	s_nop 1
	v_add_f32_dpp v19, v19, v19 quad_perm:[1,0,3,2] row_mask:0xf bank_mask:0xf bound_ctrl:1
	s_nop 1
	v_add_f32_dpp v19, v19, v19 quad_perm:[2,3,0,1] row_mask:0xf bank_mask:0xf bound_ctrl:1
	s_nop 1
	v_add_f32_dpp v19, v19, v19 row_half_mirror row_mask:0xf bank_mask:0xf bound_ctrl:1
	s_nop 1
	v_add_f32_dpp v19, v19, v19 row_mirror row_mask:0xf bank_mask:0xf bound_ctrl:1
	v_fmac_f32_e32 v6, v48, v10
	v_fmac_f32_e32 v7, v49, v11
	v_fmac_f32_e32 v8, v50, v12
	v_fmac_f32_e32 v9, v51, v13
	v_mul_f32_e32 v19, 0x3c800000, v19
	v_sub_f32_e32 v2, v2, v19
	v_sub_f32_e32 v3, v3, v19
	v_sub_f32_e32 v4, v4, v19
	v_sub_f32_e32 v5, v5, v19
	v_mul_f32_e32 v20, v2, v2
	v_mul_f32_e32 v21, v3, v3
	v_fmac_f32_e32 v20, v4, v4
	v_fmac_f32_e32 v21, v5, v5
	v_mul_f32_e32 v6, v18, v6
	v_mul_f32_e32 v7, v18, v7
	v_mul_f32_e32 v8, v18, v8
	v_mul_f32_e32 v9, v18, v9
	v_add_f32_e32 v20, v20, v21
	v_add_f32_e32 v6, v44, v6
	v_add_f32_e32 v7, v45, v7
	v_add_f32_e32 v8, v46, v8
	v_add_f32_e32 v9, v47, v9
	s_nop 1
	v_add_f32_dpp v20, v20, v20 quad_perm:[1,0,3,2] row_mask:0xf bank_mask:0xf bound_ctrl:1
	s_nop 1
	v_add_f32_dpp v20, v20, v20 quad_perm:[2,3,0,1] row_mask:0xf bank_mask:0xf bound_ctrl:1
	s_nop 1
	v_add_f32_dpp v20, v20, v20 row_half_mirror row_mask:0xf bank_mask:0xf bound_ctrl:1
	s_nop 1
	v_add_f32_dpp v20, v20, v20 row_mirror row_mask:0xf bank_mask:0xf bound_ctrl:1
	v_mov_b32_e32 v21, 0x3a27c5ac
	v_fmac_f32_e32 v21, 0x3c800000, v20
	v_rsq_f32_e32 v21, v21
	s_nop 0
	v_mul_f32_e32 v2, v2, v21
	v_mul_f32_e32 v3, v3, v21
	v_mul_f32_e32 v4, v4, v21
	v_mul_f32_e32 v5, v5, v21
	v_fmac_f32_e32 v6, v2, v40
	v_fmac_f32_e32 v7, v3, v41
	v_fmac_f32_e32 v8, v4, v42
	v_fmac_f32_e32 v9, v5, v43
	v_mul_f32_e32 v6, v6, v14
	v_mul_f32_e32 v7, v7, v15
	v_mul_f32_e32 v8, v8, v16
	v_mul_f32_e32 v9, v9, v17
	v_cvt_pk_bf16_f32 v20, v6, v7
	v_cvt_pk_bf16_f32 v21, v8, v9
	global_store_dwordx2 v72, v[20:21], s[20:21]
	s_add_u32 s20, s20, 0x2000
	s_addc_u32 s21, s21, 0
	s_waitcnt vmcnt(26)
	v_lshlrev_b32_e32 v2, 16, v120
	v_and_b32_e32 v3, 0xffff0000, v120
	v_lshlrev_b32_e32 v4, 16, v121
	v_and_b32_e32 v5, 0xffff0000, v121
	v_lshlrev_b32_e32 v6, 16, v122
	v_and_b32_e32 v7, 0xffff0000, v122
	v_lshlrev_b32_e32 v8, 16, v123
	v_and_b32_e32 v9, 0xffff0000, v123
	v_lshlrev_b32_e32 v10, 16, v124
	v_and_b32_e32 v11, 0xffff0000, v124
	v_lshlrev_b32_e32 v12, 16, v125
	v_and_b32_e32 v13, 0xffff0000, v125
	v_lshlrev_b32_e32 v14, 16, v126
	v_and_b32_e32 v15, 0xffff0000, v126
	v_lshlrev_b32_e32 v16, 16, v127
	v_and_b32_e32 v17, 0xffff0000, v127
	global_load_dwordx4 v[120:123], v73, s[22:23] nt
	global_load_dwordx4 v[124:127], v74, s[24:25]
	s_add_u32 s22, s22, 0x2000
	s_addc_u32 s23, s23, 0
	s_add_u32 s24, s24, 0x17000
	s_addc_u32 s25, s25, 0
	v_add_f32_e32 v18, v2, v3
	v_add_f32_e32 v19, v4, v5
	v_add_f32_e32 v136, v6, v7
	v_add_f32_e32 v137, v8, v9
	v_add_f32_e32 v18, v18, v19
	v_add_f32_e32 v136, v136, v137
	v_mul_f32_e32 v144, 0xbfb8aa3b, v10
	v_mul_f32_e32 v145, 0xbfb8aa3b, v11
	v_mul_f32_e32 v146, 0xbfb8aa3b, v12
	v_mul_f32_e32 v147, 0xbfb8aa3b, v13
	v_mul_f32_e32 v148, 0xbfb8aa3b, v14
	v_mul_f32_e32 v149, 0xbfb8aa3b, v15
	v_mul_f32_e32 v150, 0xbfb8aa3b, v16
	v_mul_f32_e32 v151, 0xbfb8aa3b, v17
	v_add_f32_e32 v18, v18, v136
	v_exp_f32_e32 v144, v144
	v_exp_f32_e32 v145, v145
	v_exp_f32_e32 v146, v146
	v_exp_f32_e32 v147, v147
	v_exp_f32_e32 v148, v148
	v_exp_f32_e32 v149, v149
	v_exp_f32_e32 v150, v150
	v_exp_f32_e32 v151, v151
	s_nop 1
	v_add_f32_dpp v18, v18, v18 quad_perm:[1,0,3,2] row_mask:0xf bank_mask:0xf bound_ctrl:1
	s_nop 1
	v_add_f32_dpp v18, v18, v18 quad_perm:[2,3,0,1] row_mask:0xf bank_mask:0xf bound_ctrl:1
	s_nop 1
	v_add_f32_dpp v18, v18, v18 row_half_mirror row_mask:0xf bank_mask:0xf bound_ctrl:1
	s_nop 1
	v_add_f32_dpp v18, v18, v18 row_mirror row_mask:0xf bank_mask:0xf bound_ctrl:1
	v_add_f32_e32 v144, 1.0, v144
	v_add_f32_e32 v145, 1.0, v145
	v_add_f32_e32 v146, 1.0, v146
	v_add_f32_e32 v147, 1.0, v147
	v_add_f32_e32 v148, 1.0, v148
	v_add_f32_e32 v149, 1.0, v149
	v_add_f32_e32 v150, 1.0, v150
	v_add_f32_e32 v151, 1.0, v151
	v_mul_f32_e32 v18, 0x3c000000, v18
	v_sub_f32_e32 v2, v2, v18
	v_sub_f32_e32 v3, v3, v18
	v_sub_f32_e32 v4, v4, v18
	v_sub_f32_e32 v5, v5, v18
	v_sub_f32_e32 v6, v6, v18
	v_sub_f32_e32 v7, v7, v18
	v_sub_f32_e32 v8, v8, v18
	v_sub_f32_e32 v9, v9, v18
	v_mul_f32_e32 v19, v2, v2
	v_mul_f32_e32 v136, v3, v3
	v_fmac_f32_e32 v19, v4, v4
	v_fmac_f32_e32 v136, v5, v5
	v_fmac_f32_e32 v19, v6, v6
	v_fmac_f32_e32 v136, v7, v7
	v_fmac_f32_e32 v19, v8, v8
	v_fmac_f32_e32 v136, v9, v9
	v_rcp_f32_e32 v144, v144
	v_rcp_f32_e32 v145, v145
	v_rcp_f32_e32 v146, v146
	v_rcp_f32_e32 v147, v147
	v_rcp_f32_e32 v148, v148
	v_rcp_f32_e32 v149, v149
	v_rcp_f32_e32 v150, v150
	v_rcp_f32_e32 v151, v151
	v_add_f32_e32 v19, v19, v136
	s_nop 1
	v_add_f32_dpp v19, v19, v19 quad_perm:[1,0,3,2] row_mask:0xf bank_mask:0xf bound_ctrl:1
	s_nop 1
	v_add_f32_dpp v19, v19, v19 quad_perm:[2,3,0,1] row_mask:0xf bank_mask:0xf bound_ctrl:1
	s_nop 1
	v_add_f32_dpp v19, v19, v19 row_half_mirror row_mask:0xf bank_mask:0xf bound_ctrl:1
	s_nop 1
	v_add_f32_dpp v19, v19, v19 row_mirror row_mask:0xf bank_mask:0xf bound_ctrl:1
	v_mul_f32_e32 v10, v10, v144
	v_mul_f32_e32 v11, v11, v145
	v_mul_f32_e32 v12, v12, v146
	v_mul_f32_e32 v13, v13, v147
	v_mul_f32_e32 v14, v14, v148
	v_mul_f32_e32 v15, v15, v149
	v_mul_f32_e32 v16, v16, v150
	v_mul_f32_e32 v17, v17, v151
	v_mov_b32_e32 v136, 0x3727c5ac
	v_fmac_f32_e32 v136, 0x3c000000, v19
	v_rsq_f32_e32 v136, v136
	s_nop 0
	v_mul_f32_e32 v2, v2, v136
	v_mul_f32_e32 v3, v3, v136
	v_mul_f32_e32 v4, v4, v136
	v_mul_f32_e32 v5, v5, v136
	v_mul_f32_e32 v6, v6, v136
	v_mul_f32_e32 v7, v7, v136
	v_mul_f32_e32 v8, v8, v136
	v_mul_f32_e32 v9, v9, v136
	v_fma_f32 v2, v2, v52, v60
	v_fma_f32 v3, v3, v53, v61
	v_fma_f32 v4, v4, v54, v62
	v_fma_f32 v5, v5, v55, v63
	v_fma_f32 v6, v6, v56, v64
	v_fma_f32 v7, v7, v57, v65
	v_fma_f32 v8, v8, v58, v66
	v_fma_f32 v9, v9, v59, v67
	v_mul_f32_e32 v2, v2, v10
	v_mul_f32_e32 v3, v3, v11
	v_mul_f32_e32 v4, v4, v12
	v_mul_f32_e32 v5, v5, v13
	v_mul_f32_e32 v6, v6, v14
	v_mul_f32_e32 v7, v7, v15
	v_mul_f32_e32 v8, v8, v16
	v_mul_f32_e32 v9, v9, v17
	v_cvt_pk_bf16_f32 v136, v2, v3
	v_cvt_pk_bf16_f32 v137, v4, v5
	v_cvt_pk_bf16_f32 v138, v6, v7
	v_cvt_pk_bf16_f32 v139, v8, v9
	global_store_dwordx4 v75, v[136:139], s[26:27]
	s_add_u32 s26, s26, 0x4000
	s_addc_u32 s27, s27, 0
	s_waitcnt vmcnt(27)
	v_lshlrev_b32_e32 v2, 16, v128
	v_and_b32_e32 v3, 0xffff0000, v128
	v_lshlrev_b32_e32 v4, 16, v129
	v_and_b32_e32 v5, 0xffff0000, v129
	v_lshlrev_b32_e32 v6, 16, v130
	v_and_b32_e32 v7, 0xffff0000, v130
	v_lshlrev_b32_e32 v8, 16, v131
	v_and_b32_e32 v9, 0xffff0000, v131
	v_lshlrev_b32_e32 v10, 16, v132
	v_and_b32_e32 v11, 0xffff0000, v132
	v_lshlrev_b32_e32 v12, 16, v133
	v_and_b32_e32 v13, 0xffff0000, v133
	v_lshlrev_b32_e32 v14, 16, v134
	v_and_b32_e32 v15, 0xffff0000, v134
	v_lshlrev_b32_e32 v16, 16, v135
	v_and_b32_e32 v17, 0xffff0000, v135
	global_load_dwordx4 v[128:131], v73, s[22:23] nt
	global_load_dwordx4 v[132:135], v74, s[24:25]
	s_add_u32 s22, s22, 0x2000
	s_addc_u32 s23, s23, 0
	s_add_u32 s24, s24, 0x17000
	s_addc_u32 s25, s25, 0
	v_add_f32_e32 v18, v2, v3
	v_add_f32_e32 v19, v4, v5
	v_add_f32_e32 v136, v6, v7
	v_add_f32_e32 v137, v8, v9
	v_add_f32_e32 v18, v18, v19
	v_add_f32_e32 v136, v136, v137
	v_mul_f32_e32 v144, 0xbfb8aa3b, v10
	v_mul_f32_e32 v145, 0xbfb8aa3b, v11
	v_mul_f32_e32 v146, 0xbfb8aa3b, v12
	v_mul_f32_e32 v147, 0xbfb8aa3b, v13
	v_mul_f32_e32 v148, 0xbfb8aa3b, v14
	v_mul_f32_e32 v149, 0xbfb8aa3b, v15
	v_mul_f32_e32 v150, 0xbfb8aa3b, v16
	v_mul_f32_e32 v151, 0xbfb8aa3b, v17
	v_add_f32_e32 v18, v18, v136
	v_exp_f32_e32 v144, v144
	v_exp_f32_e32 v145, v145
	v_exp_f32_e32 v146, v146
	v_exp_f32_e32 v147, v147
	v_exp_f32_e32 v148, v148
	v_exp_f32_e32 v149, v149
	v_exp_f32_e32 v150, v150
	v_exp_f32_e32 v151, v151
	s_nop 1
	v_add_f32_dpp v18, v18, v18 quad_perm:[1,0,3,2] row_mask:0xf bank_mask:0xf bound_ctrl:1
	s_nop 1
	v_add_f32_dpp v18, v18, v18 quad_perm:[2,3,0,1] row_mask:0xf bank_mask:0xf bound_ctrl:1
	s_nop 1
	v_add_f32_dpp v18, v18, v18 row_half_mirror row_mask:0xf bank_mask:0xf bound_ctrl:1
	s_nop 1
	v_add_f32_dpp v18, v18, v18 row_mirror row_mask:0xf bank_mask:0xf bound_ctrl:1
	v_add_f32_e32 v144, 1.0, v144
	v_add_f32_e32 v145, 1.0, v145
	v_add_f32_e32 v146, 1.0, v146
	v_add_f32_e32 v147, 1.0, v147
	v_add_f32_e32 v148, 1.0, v148
	v_add_f32_e32 v149, 1.0, v149
	v_add_f32_e32 v150, 1.0, v150
	v_add_f32_e32 v151, 1.0, v151
	v_mul_f32_e32 v18, 0x3c000000, v18
	v_sub_f32_e32 v2, v2, v18
	v_sub_f32_e32 v3, v3, v18
	v_sub_f32_e32 v4, v4, v18
	v_sub_f32_e32 v5, v5, v18
	v_sub_f32_e32 v6, v6, v18
	v_sub_f32_e32 v7, v7, v18
	v_sub_f32_e32 v8, v8, v18
	v_sub_f32_e32 v9, v9, v18
	v_mul_f32_e32 v19, v2, v2
	v_mul_f32_e32 v136, v3, v3
	v_fmac_f32_e32 v19, v4, v4
	v_fmac_f32_e32 v136, v5, v5
	v_fmac_f32_e32 v19, v6, v6
	v_fmac_f32_e32 v136, v7, v7
	v_fmac_f32_e32 v19, v8, v8
	v_fmac_f32_e32 v136, v9, v9
	v_rcp_f32_e32 v144, v144
	v_rcp_f32_e32 v145, v145
	v_rcp_f32_e32 v146, v146
	v_rcp_f32_e32 v147, v147
	v_rcp_f32_e32 v148, v148
	v_rcp_f32_e32 v149, v149
	v_rcp_f32_e32 v150, v150
	v_rcp_f32_e32 v151, v151
	v_add_f32_e32 v19, v19, v136
	s_nop 1
	v_add_f32_dpp v19, v19, v19 quad_perm:[1,0,3,2] row_mask:0xf bank_mask:0xf bound_ctrl:1
	s_nop 1
	v_add_f32_dpp v19, v19, v19 quad_perm:[2,3,0,1] row_mask:0xf bank_mask:0xf bound_ctrl:1
	s_nop 1
	v_add_f32_dpp v19, v19, v19 row_half_mirror row_mask:0xf bank_mask:0xf bound_ctrl:1
	s_nop 1
	v_add_f32_dpp v19, v19, v19 row_mirror row_mask:0xf bank_mask:0xf bound_ctrl:1
	v_mul_f32_e32 v10, v10, v144
	v_mul_f32_e32 v11, v11, v145
	v_mul_f32_e32 v12, v12, v146
	v_mul_f32_e32 v13, v13, v147
	v_mul_f32_e32 v14, v14, v148
	v_mul_f32_e32 v15, v15, v149
	v_mul_f32_e32 v16, v16, v150
	v_mul_f32_e32 v17, v17, v151
	v_mov_b32_e32 v136, 0x3727c5ac
	v_fmac_f32_e32 v136, 0x3c000000, v19
	v_rsq_f32_e32 v136, v136
	s_nop 0
	v_mul_f32_e32 v2, v2, v136
	v_mul_f32_e32 v3, v3, v136
	v_mul_f32_e32 v4, v4, v136
	v_mul_f32_e32 v5, v5, v136
	v_mul_f32_e32 v6, v6, v136
	v_mul_f32_e32 v7, v7, v136
	v_mul_f32_e32 v8, v8, v136
	v_mul_f32_e32 v9, v9, v136
	v_fma_f32 v2, v2, v52, v60
	v_fma_f32 v3, v3, v53, v61
	v_fma_f32 v4, v4, v54, v62
	v_fma_f32 v5, v5, v55, v63
	v_fma_f32 v6, v6, v56, v64
	v_fma_f32 v7, v7, v57, v65
	v_fma_f32 v8, v8, v58, v66
	v_fma_f32 v9, v9, v59, v67
	v_mul_f32_e32 v2, v2, v10
	v_mul_f32_e32 v3, v3, v11
	v_mul_f32_e32 v4, v4, v12
	v_mul_f32_e32 v5, v5, v13
	v_mul_f32_e32 v6, v6, v14
	v_mul_f32_e32 v7, v7, v15
	v_mul_f32_e32 v8, v8, v16
	v_mul_f32_e32 v9, v9, v17
	v_cvt_pk_bf16_f32 v136, v2, v3
	v_cvt_pk_bf16_f32 v137, v4, v5
	v_cvt_pk_bf16_f32 v138, v6, v7
	v_cvt_pk_bf16_f32 v139, v8, v9
	global_store_dwordx4 v75, v[136:139], s[26:27]
	s_add_u32 s26, s26, 0x4000
	s_addc_u32 s27, s27, 0
	s_add_u32 s10, s10, 0x3fc000
	s_addc_u32 s11, s11, 0
	s_add_u32 s12, s12, 0x3fc000
	s_addc_u32 s13, s13, 0
	s_add_u32 s14, s14, 0x2dd2000
	s_addc_u32 s15, s15, 0
	s_add_u32 s16, s16, 0x2dd2000
	s_addc_u32 s17, s17, 0
	s_add_u32 s18, s18, 0x1fe00
	s_addc_u32 s19, s19, 0
	s_add_u32 s22, s22, 0x3fc000
	s_addc_u32 s23, s23, 0
	s_add_u32 s24, s24, 0x2dd2000
	s_addc_u32 s25, s25, 0
	s_add_u32 s20, s20, 0x7f8000
	s_addc_u32 s21, s21, 0
	s_add_u32 s26, s26, 0x7f8000
	s_addc_u32 s27, s27, 0
	s_sub_u32 s30, s30, 1
	s_cmp_lg_u32 s30, 0
	s_cbranch_scc1 .Lpost_step
	s_waitcnt vmcnt(0)
	s_add_i32 s8, s8, 0x2000
.Lpost_orig:
	s_cmpk_gt_i32 s8, 0x20ff
	s_cbranch_scc1 .LBB0_1915
	v_and_b32_e32 v1, 0x3c0, v34
	s_waitcnt vmcnt(0)
	v_add_u32_e32 v16, v1, v34
	v_mov_b32_e32 v19, 0
	v_lshlrev_b32_e32 v18, 2, v16
	v_lshl_add_u64 v[2:3], s[58:59], 0, v[18:19]
	s_movk_i32 s0, 0x2000
	v_readlane_b32 s12, v254, 21
	v_add_co_u32_e32 v2, vcc, s0, v2
	v_readlane_b32 s13, v254, 22
	v_readlane_b32 s14, v254, 23
	v_readlane_b32 s15, v254, 24
	v_readlane_b32 s16, v254, 25
	v_readlane_b32 s17, v254, 26
	v_readlane_b32 s18, v254, 27
	v_readlane_b32 s19, v254, 28
	v_readlane_b32 s20, v254, 29
	v_readlane_b32 s21, v254, 30
	v_addc_co_u32_e32 v3, vcc, 0, v3, vcc
	v_readlane_b32 s22, v254, 31
	v_readlane_b32 s23, v254, 32
	v_readlane_b32 s24, v254, 33
	v_readlane_b32 s25, v254, 34
	v_readlane_b32 s26, v254, 35
	v_readlane_b32 s27, v254, 36
	s_mov_b64 s[12:13], s[20:21]
	global_load_dword v17, v[2:3], off
	global_load_dword v21, v[2:3], off offset:256
	s_mov_b64 s[14:15], s[22:23]
	s_mov_b64 s[16:17], s[24:25]
	s_mov_b64 s[18:19], s[26:27]
	global_load_dword v62, v18, s[12:13]
	global_load_dword v63, v18, s[12:13] offset:256
	global_load_dword v64, v18, s[14:15]
	global_load_dword v65, v18, s[14:15] offset:256
	global_load_dword v66, v18, s[16:17]
	global_load_dword v67, v18, s[16:17] offset:256
	global_load_dword v68, v18, s[18:19] offset:256
	global_load_dword v69, v18, s[18:19]
	v_lshrrev_b32_e32 v1, 3, v34
	s_add_u32 s3, s34, 0xd322200
	v_and_b32_e32 v18, 0x78, v1
	v_lshrrev_b32_e32 v1, 9, v34
	s_addc_u32 s4, s35, 0
	v_lshl_add_u64 v[2:3], s[34:35], 0, v[18:19]
	s_mov_b64 s[0:1], 0x8a70200
	v_sub_u32_e32 v1, 32, v1
	v_lshlrev_b32_e32 v18, 1, v16
	s_add_u32 s10, s34, 0xb222200
	v_lshl_add_u64 v[22:23], v[2:3], 0, s[0:1]
	v_and_b32_e32 v70, 60, v1
	v_lshl_add_u64 v[2:3], s[34:35], 0, v[18:19]
	s_mov_b64 s[12:13], 0x9122200
	s_addc_u32 s11, s35, 0
	v_cmp_ne_u32_e64 s[0:1], v1, v70
	v_lshl_add_u64 v[24:25], v[2:3], 0, s[12:13]
	s_mov_b64 s[12:13], 0x1d2e2200
	v_lshl_or_b32 v1, v70, 9, v34
	v_lshl_add_u64 v[26:27], v[2:3], 0, s[12:13]
	v_lshl_add_u64 v[28:29], s[82:83], 0, v[18:19]
	v_lshl_add_u64 v[30:31], s[10:11], 0, v[18:19]
	s_mov_b64 s[12:13], 0xb222a00
	v_lshlrev_b32_e32 v18, 1, v1
	s_mov_b64 s[6:7], 0xb222200
	v_lshl_add_u64 v[32:33], v[2:3], 0, s[12:13]
	v_lshl_add_u64 v[2:3], s[34:35], 0, v[18:19]
	s_mov_b32 s12, 0x3c800000
	s_mov_b32 s14, 0x3a27c5ac
	v_or_b32_e32 v20, 64, v16
	s_mov_b32 s5, 0
	s_lshl_b32 s30, s88, 3
	v_add_u32_e32 v37, 0x600, v34
	v_or_b32_e32 v36, 0x400, v34
	v_add_u32_e32 v35, 0x200, v34
	v_add_u32_e32 v71, 0xfffffe00, v1
	v_lshl_add_u64 v[38:39], v[2:3], 0, s[6:7]
	s_brev_b32 s13, 60
	s_mov_b32 s15, 0x3727c5ac
	s_mov_b32 s33, 0x800000
	s_movk_i32 s44, 0x7fff
	s_mov_b64 s[16:17], 0x400
	s_movk_i32 s45, 0x3dff
	s_branch .LBB0_1872

.LBB0_2016:
	s_sub_u32 s32, s28, 32
	v_readfirstlane_b32 s2, v34
	s_cmp_lt_u32 s32, 32
	s_cbranch_scc0 .LBB0_2024
	s_lshl_b32 s1, s32, 5
	s_and_b32 s10, s1, 0xffffff00
	s_lshr_b32 s0, s2, 6
	s_ashr_i32 s11, s10, 31
	s_lshr_b32 s8, s2, 8
	s_lshl_b32 s12, s0, 10
	s_lshl_b64 s[10:11], s[10:11], 1
	s_add_u32 s1, s10, 0x800
	s_addc_u32 s9, s11, 0
	s_lshl_b32 s10, s5, 20
	s_add_u32 s10, s3, s10
	s_addc_u32 s11, s4, 0
	s_add_u32 s20, s10, s1
	s_addc_u32 s21, s11, s9
	s_add_i32 s24, s12, 0
	s_add_i32 m0, s24, 0x10000
	v_mov_b32_e32 v3, 0
	global_load_lds_dwordx4 v136, s[20:21]
	s_add_i32 m0, s24, 0x12000
	s_add_u32 s25, s34, 0xd222200
	s_addc_u32 s26, s35, 0
	s_add_u32 s18, s25, s1
	global_load_lds_dwordx4 v138, s[20:21]
	s_addc_u32 s19, s26, s9
	s_mov_b32 m0, s24
	s_add_i32 s27, s24, 0x2000
	global_load_lds_dwordx4 v136, s[18:19]
	s_mov_b32 m0, s27
	s_add_u32 s10, s20, 0x80000
	global_load_lds_dwordx4 v138, s[18:19]
	s_addc_u32 s11, s21, 0
	s_add_i32 m0, s24, 0x14000
	v_mov_b32_e32 v137, v3
	global_load_lds_dwordx4 v136, s[10:11]
	s_add_i32 m0, s24, 0x16000
	v_mov_b32_e32 v139, v3
	global_load_lds_dwordx4 v138, s[10:11]
	s_add_u32 s10, s18, 0x80000
	s_addc_u32 s11, s19, 0
	s_add_i32 s29, s24, 0x4000
	s_mov_b32 m0, s29
	s_add_i32 s30, s24, 0x6000
	global_load_lds_dwordx4 v136, s[10:11]
	s_mov_b32 m0, s30
	v_lshl_add_u64 v[10:11], s[20:21], 0, v[136:137]
	global_load_lds_dwordx4 v138, s[10:11]
	v_lshl_add_u64 v[8:9], s[20:21], 0, v[138:139]
	v_lshl_add_u64 v[6:7], s[18:19], 0, v[136:137]
	s_cmp_lg_u32 s8, 1
	v_lshl_add_u64 v[4:5], s[18:19], 0, v[138:139]
	s_cbranch_scc1 .LBB0_2019
	s_barrier
.LBB0_2019:
	s_add_u32 s10, s34, 0x1eca2200
	s_addc_u32 s11, s35, 0
	s_lshl_b32 s0, s0, 5
	s_and_b32 s13, s0, 0x60
	s_mov_b64 s[0:1], 0x80
	s_add_i32 m0, s24, 0x18000
	v_lshl_add_u64 v[10:11], v[10:11], 0, s[0:1]
	s_lshl_b32 s9, s8, 13
	s_waitcnt vmcnt(4)
	s_barrier
	global_load_lds_dwordx4 v[10:11], off
	v_lshl_add_u64 v[8:9], v[8:9], 0, s[0:1]
	s_add_i32 m0, s24, 0x1a000
	s_add_i32 s31, s24, 0x8000
	s_add_i32 s33, s24, 0xa000
	global_load_lds_dwordx4 v[8:9], off
	v_lshl_add_u64 v[6:7], v[6:7], 0, s[0:1]
	s_mov_b32 m0, s31
	s_add_u32 s14, s20, 0x80080
	global_load_lds_dwordx4 v[6:7], off
	v_lshl_add_u64 v[4:5], v[4:5], 0, s[0:1]
	s_mov_b32 m0, s33
	s_addc_u32 s15, s21, 0
	global_load_lds_dwordx4 v[4:5], off
	s_add_i32 m0, s24, 0x1c000
	v_lshl_add_u64 v[4:5], s[14:15], 0, v[136:137]
	global_load_lds_dwordx4 v[4:5], off
	v_lshl_add_u64 v[4:5], s[14:15], 0, v[138:139]
	s_add_i32 m0, s24, 0x1e000
	v_lshl_or_b32 v2, s8, 6, v166
	global_load_lds_dwordx4 v[4:5], off
	v_lshlrev_b32_e32 v5, 2, v166
	v_lshl_or_b32 v4, v166, 6, v167
	v_and_b32_e32 v5, 32, v5
	v_bitop3_b32 v14, v4, s9, v5 bitop3:0xde
	v_lshl_or_b32 v17, s13, 7, v35
	s_waitcnt vmcnt(6)
	v_lshlrev_b64 v[4:5], 13, v[2:3]
	v_or_b32_e32 v6, 16, v2
	v_mov_b32_e32 v7, v3
	v_or_b32_e32 v8, 32, v2
	v_mov_b32_e32 v9, v3
	v_or_b32_e32 v2, 48, v2
	s_add_i32 s44, 0, 0x10000
	s_add_i32 s46, 0, 0x14000
	s_add_i32 s48, 0, 0x18000
	s_add_i32 s52, 0, 0x1c000
	v_lshlrev_b64 v[6:7], 13, v[6:7]
	v_lshlrev_b64 v[8:9], 13, v[8:9]
	v_lshlrev_b64 v[10:11], 13, v[2:3]
	s_add_i32 s8, s32, s88
	v_add_u32_e32 v13, s44, v17
	v_add_u32_e32 v15, s46, v17
	s_add_i32 s44, s44, s12
	s_add_i32 s46, s46, s12
	v_add_u32_e32 v16, s48, v17
	v_add_u32_e32 v17, s52, v17
	s_add_i32 s48, s48, s12
	s_add_i32 s52, s52, s12
	v_lshl_add_u64 v[4:5], s[10:11], 0, v[4:5]
	v_lshl_add_u64 v[6:7], s[10:11], 0, v[6:7]
	v_lshl_add_u64 v[8:9], s[10:11], 0, v[8:9]
	v_lshl_add_u64 v[10:11], s[10:11], 0, v[10:11]
	v_lshl_or_b32 v12, v1, 2, s13
	s_lshl_b32 s40, s8, 5
	s_lshl_b32 s41, s88, 5
	v_add_u32_e32 v14, 0, v14
	s_add_i32 s42, s24, 0xc000
	s_add_i32 s43, s24, 0xe000
	s_mov_b64 s[8:9], 0x100
	s_add_i32 s45, s44, 0x2000
	s_add_i32 s47, s46, 0x2000
	s_mov_b64 s[10:11], 0x180
	s_add_i32 s49, s48, 0x2000
	s_add_i32 s53, s52, 0x2000
	s_mov_b32 s54, s32
	s_barrier

.LBB0_2255:
	s_or_b64 exec, exec, s[0:1]
	v_readfirstlane_b32 s72, v88
	v_readfirstlane_b32 s73, v89
	s_add_u32 s74, s72, 0x7000
	s_addc_u32 s75, s73, 0
	s_add_u32 s72, s72, 0x9000
	s_addc_u32 s73, s73, 0
	global_load_dwordx4 v[238:241], v40, s[72:73] offset:-4096
	global_load_dwordx4 v[242:245], v40, s[74:75] offset:-4096
	global_load_dwordx4 v[246:249], v40, s[72:73] offset:-3072
	global_load_dwordx4 v[250:253], v40, s[74:75] offset:-3072
	global_load_dwordx4 v[158:161], v40, s[72:73] offset:-2048
	global_load_dwordx4 v[162:165], v40, s[74:75] offset:-2048
	v_mov_b32_e32 v94, v6
	v_mov_b32_e32 v95, v2
	v_mov_b32_e32 v96, v7
	v_mov_b32_e32 v97, v3
	v_pk_add_f32 v[94:95], v[94:95], v[96:97]
	v_mov_b32_e32 v96, v8
	v_mov_b32_e32 v97, v4
	v_mov_b32_e32 v98, v9
	v_mov_b32_e32 v99, v5
	v_pk_add_f32 v[96:97], v[96:97], v[98:99]
	v_mov_b32_e32 v98, v10
	v_pk_add_f32 v[94:95], v[94:95], v[96:97]
	v_mov_b32_e32 v96, v11
	v_mov_b32_e32 v97, v12
	v_mov_b32_e32 v99, v13
	v_pk_add_f32 v[96:97], v[96:97], v[98:99]
	v_add_f32_e32 v39, 0, v95
	v_pk_add_f32 v[96:97], v[96:97], v[96:97] op_sel_hi:[0,1]
	v_add_f32_e32 v95, v94, v39
	v_add_f32_e32 v99, v14, v15
	v_add_f32_e32 v101, v16, v17
	v_mov_b32_e32 v98, v18
	v_mov_b32_e32 v100, v19
	v_mov_b32_e32 v96, v20
	v_mov_b32_e32 v94, v21
	v_pk_add_f32 v[98:99], v[98:99], v[100:101]
	v_pk_add_f32 v[94:95], v[96:97], v[94:95]
	v_mov_b32_e32 v96, v23
	v_pk_add_f32 v[94:95], v[98:99], v[94:95]
	v_mov_b32_e32 v97, v24
	v_mov_b32_e32 v98, v22
	v_mov_b32_e32 v99, v25
	v_pk_add_f32 v[96:97], v[96:97], v[98:99]
	v_pk_add_f32 v[94:95], v[94:95], v[94:95] op_sel_hi:[0,1]
	v_pk_add_f32 v[96:97], v[96:97], v[96:97] op_sel_hi:[0,1]
	v_add_f32_e32 v99, v26, v27
	v_add_f32_e32 v101, v28, v29
	v_mov_b32_e32 v98, v30
	v_mov_b32_e32 v100, v31
	v_mov_b32_e32 v96, v32
	v_mov_b32_e32 v94, v33
	v_pk_add_f32 v[98:99], v[98:99], v[100:101]
	v_pk_add_f32 v[94:95], v[96:97], v[94:95]
	v_mov_b32_e32 v93, v41
	v_pk_add_f32 v[94:95], v[98:99], v[94:95]
	s_nop 0
	v_add_f32_e32 v39, v94, v95
	s_nop 1
	v_add_f32_dpp v39, v39, v39 quad_perm:[1,0,3,2] row_mask:0xf bank_mask:0xf bound_ctrl:1
	s_nop 1
	v_add_f32_dpp v39, v39, v39 quad_perm:[2,3,0,1] row_mask:0xf bank_mask:0xf bound_ctrl:1
	s_nop 1
	v_add_f32_dpp v39, v39, v39 row_half_mirror row_mask:0xf bank_mask:0xf bound_ctrl:1
	s_nop 1
	v_add_f32_dpp v39, v39, v39 row_mirror row_mask:0xf bank_mask:0xf bound_ctrl:1
	s_nop 0
	v_readlane_b32 s2, v39, 16
	v_readlane_b32 s21, v39, 48
	v_readlane_b32 s0, v39, 0
	v_readlane_b32 s1, v39, 32
	v_mov_b32_e32 v94, s2
	v_mov_b32_e32 v95, s21
	v_pk_add_f32 v[94:95], s[0:1], v[94:95]
	s_nop 0
	v_add_f32_e32 v39, v94, v95
	v_fmamk_f32 v121, v39, 0xba000000, v5
	v_fmamk_f32 v123, v39, 0xba000000, v3
	v_fmamk_f32 v120, v39, 0xba000000, v4
	v_fmamk_f32 v122, v39, 0xba000000, v2
	v_fmamk_f32 v105, v39, 0xba000000, v9
	v_fmamk_f32 v107, v39, 0xba000000, v7
	v_mov_b32_e32 v106, v123
	v_mov_b32_e32 v104, v121
	v_fmamk_f32 v109, v39, 0xba000000, v8
	v_fmamk_f32 v111, v39, 0xba000000, v6
	v_mov_b32_e32 v110, v122
	v_pk_mul_f32 v[2:3], v[106:107], v[106:107]
	v_mov_b32_e32 v108, v120
	v_pk_mul_f32 v[4:5], v[104:105], v[104:105]
	v_pk_fma_f32 v[2:3], v[110:111], v[110:111], v[2:3]
	v_pk_fma_f32 v[4:5], v[108:109], v[108:109], v[4:5]
	v_fmamk_f32 v99, v39, 0xba000000, v13
	v_pk_add_f32 v[2:3], v[2:3], v[4:5]
	v_fmamk_f32 v98, v39, 0xba000000, v12
	v_pk_add_f32 v[6:7], v[2:3], v[2:3] op_sel_hi:[0,1]
	v_fmamk_f32 v103, v39, 0xba000000, v11
	v_fmamk_f32 v102, v39, 0xba000000, v10
	v_pk_mul_f32 v[8:9], v[98:99], v[98:99]
	v_pk_mul_f32 v[10:11], v[102:103], v[102:103]
	v_fmamk_f32 v114, v39, 0xba000000, v14
	v_pk_mov_b32 v[12:13], v[10:11], v[8:9] op_sel:[1,0]
	v_mov_b32_e32 v11, v9
	v_fmamk_f32 v112, v39, 0xba000000, v16
	v_fmamk_f32 v115, v39, 0xba000000, v15
	v_mul_f32_e32 v6, v114, v114
	v_pk_add_f32 v[8:9], v[12:13], v[10:11]
	v_fmamk_f32 v113, v39, 0xba000000, v17
	v_pk_fma_f32 v[10:11], v[114:115], v[114:115], v[6:7] op_sel_hi:[1,1,0]
	v_mul_f32_e32 v6, v112, v112
	v_pk_add_f32 v[8:9], v[8:9], v[8:9] op_sel_hi:[0,1]
	v_pk_fma_f32 v[12:13], v[112:113], v[112:113], v[6:7] op_sel_hi:[1,1,0]
	v_fmamk_f32 v97, v39, 0xba000000, v21
	v_fmamk_f32 v96, v39, 0xba000000, v20
	v_fmamk_f32 v101, v39, 0xba000000, v19
	v_fmamk_f32 v100, v39, 0xba000000, v18
	v_mul_f32_e32 v10, v100, v100
	v_mul_f32_e32 v12, v101, v101
	v_mul_f32_e32 v8, v96, v96
	v_mul_f32_e32 v6, v97, v97
	v_pk_add_f32 v[10:11], v[10:11], v[12:13]
	v_pk_add_f32 v[6:7], v[8:9], v[6:7]
	v_fmamk_f32 v25, v39, 0xba000000, v25
	v_pk_add_f32 v[6:7], v[10:11], v[6:7]
	v_fmamk_f32 v24, v39, 0xba000000, v24
	v_fmamk_f32 v95, v39, 0xba000000, v23
	v_fmamk_f32 v94, v39, 0xba000000, v22
	v_pk_add_f32 v[8:9], v[6:7], v[6:7] op_sel_hi:[0,1]
	v_pk_mul_f32 v[6:7], v[24:25], v[24:25]
	v_pk_mul_f32 v[10:11], v[94:95], v[94:95]
	v_fmamk_f32 v22, v39, 0xba000000, v26
	v_pk_mov_b32 v[12:13], v[10:11], v[6:7] op_sel:[1,0]
	v_mov_b32_e32 v11, v7
	v_pk_add_f32 v[6:7], v[12:13], v[10:11]
	v_fmamk_f32 v20, v39, 0xba000000, v28
	v_pk_add_f32 v[10:11], v[6:7], v[6:7] op_sel_hi:[0,1]
	v_fmamk_f32 v23, v39, 0xba000000, v27
	v_mul_f32_e32 v6, v22, v22
	v_fmamk_f32 v21, v39, 0xba000000, v29
	v_pk_fma_f32 v[12:13], v[22:23], v[22:23], v[6:7] op_sel_hi:[1,1,0]
	v_mul_f32_e32 v6, v20, v20
	v_pk_fma_f32 v[14:15], v[20:21], v[20:21], v[6:7] op_sel_hi:[1,1,0]
	v_fmamk_f32 v7, v39, 0xba000000, v33
	v_fmamk_f32 v6, v39, 0xba000000, v32
	v_fmamk_f32 v31, v39, 0xba000000, v31
	v_fmac_f32_e32 v30, 0xba000000, v39
	v_mul_f32_e32 v12, v30, v30
	v_mul_f32_e32 v14, v31, v31
	v_mul_f32_e32 v10, v6, v6
	v_mul_f32_e32 v8, v7, v7
	v_pk_add_f32 v[12:13], v[12:13], v[14:15]
	v_pk_add_f32 v[8:9], v[10:11], v[8:9]
	v_lshlrev_b64 v[18:19], 11, v[36:37]
	v_pk_add_f32 v[8:9], v[12:13], v[8:9]
	s_nop 0
	v_add_f32_e32 v8, v8, v9
	s_nop 1
	v_add_f32_dpp v8, v8, v8 quad_perm:[1,0,3,2] row_mask:0xf bank_mask:0xf bound_ctrl:1
	s_nop 1
	v_add_f32_dpp v8, v8, v8 quad_perm:[2,3,0,1] row_mask:0xf bank_mask:0xf bound_ctrl:1
	s_nop 1
	v_add_f32_dpp v8, v8, v8 row_half_mirror row_mask:0xf bank_mask:0xf bound_ctrl:1
	s_nop 1
	v_add_f32_dpp v8, v8, v8 row_mirror row_mask:0xf bank_mask:0xf bound_ctrl:1
	s_nop 0
	v_readlane_b32 s2, v8, 16
	v_readlane_b32 s21, v8, 48
	v_readlane_b32 s0, v8, 0
	v_readlane_b32 s1, v8, 32
	v_mov_b32_e32 v8, s2
	v_mov_b32_e32 v9, s21
	v_pk_add_f32 v[8:9], s[0:1], v[8:9]
	s_nop 0
	v_add_f32_e32 v8, v8, v9
	v_fmamk_f32 v8, v8, 0x3a000000, v35
	v_mul_f32_e32 v9, 0x4b800000, v8
	v_cmp_gt_f32_e32 vcc, s33, v8
	s_nop 1
	v_cndmask_b32_e32 v8, v8, v9, vcc
	v_rsq_f32_e32 v10, v8
	v_lshl_add_u64 v[8:9], v[18:19], 2, s[82:83]
	v_mul_f32_e32 v11, 0x45800000, v10
	v_cndmask_b32_e32 v10, v10, v11, vcc
	v_pk_mul_f32 v[12:13], v[122:123], v[10:11] op_sel_hi:[1,0]
	v_pk_mul_f32 v[14:15], v[120:121], v[10:11] op_sel_hi:[1,0]
	v_cmp_lt_i32_e32 vcc, s5, v36
	v_mov_b32_e32 v2, v174
	v_mov_b32_e32 v3, v175
	v_mov_b32_e32 v4, v176
	v_mov_b32_e32 v5, v177
	v_mov_b32_e32 v116, v178
	v_mov_b32_e32 v117, v179
	v_mov_b32_e32 v118, v180
	v_mov_b32_e32 v119, v181
	v_pk_fma_f32 v[4:5], v[4:5], v[14:15], v[118:119]
	v_pk_fma_f32 v[2:3], v[2:3], v[12:13], v[116:117]
	v_lshl_add_u64 v[14:15], v[90:91], 0, v[92:93]
	v_cvt_pk_bf16_f32 v12, v2, v3
	v_cvt_pk_bf16_f32 v13, v4, v5
	global_store_dwordx2 v[14:15], v[12:13], off nt
	s_and_saveexec_b64 s[0:1], vcc
	s_cbranch_execz .LBB0_2257
	v_lshl_add_u64 v[12:13], v[8:9], 0, v[40:41]
	global_store_dwordx4 v[12:13], v[2:5], off
.LBB0_2257:
	s_or_b64 exec, exec, s[0:1]
	v_lshl_add_u64 v[16:17], v[88:89], 0, s[22:23]
	v_lshl_add_u64 v[12:13], v[88:89], 0, s[24:25]
	v_lshl_add_u64 v[26:27], v[16:17], 0, v[40:41]
	v_lshl_add_u64 v[32:33], v[12:13], 0, v[40:41]
	v_lshl_add_u64 v[18:19], v[18:19], 1, v[42:43]
	v_mov_b32_e32 v106, v111
	v_mov_b32_e32 v11, v10
	v_mov_b32_e32 v104, v109
	v_pk_mul_f32 v[32:33], v[106:107], v[10:11]
	s_waitcnt vmcnt(5)
	v_mov_b32_e32 v26, v238
	v_mov_b32_e32 v27, v239
	v_mov_b32_e32 v28, v240
	v_mov_b32_e32 v29, v241
	v_mov_b32_e32 v88, v242
	v_mov_b32_e32 v89, v243
	v_mov_b32_e32 v90, v244
	v_mov_b32_e32 v91, v245
	global_load_dwordx4 v[238:241], v40, s[72:73] offset:-1024
	global_load_dwordx4 v[242:245], v40, s[74:75] offset:-1024
	v_pk_add_f32 v[26:27], v[26:27], 1.0 op_sel_hi:[1,0]
	v_pk_add_f32 v[28:29], v[28:29], 1.0 op_sel_hi:[1,0]
	v_pk_fma_f32 v[2:3], v[2:3], v[26:27], v[88:89]
	v_pk_fma_f32 v[4:5], v[4:5], v[28:29], v[90:91]
	v_cvt_pk_bf16_f32 v2, v2, v3
	v_mov_b32_e32 v26, v10
	v_cvt_pk_bf16_f32 v3, v4, v5
	global_store_dwordx2 v[18:19], v[2:3], off
	s_nop 0
	v_mov_b32_e32 v27, v10
	v_pk_mul_f32 v[28:29], v[104:105], v[26:27]
	v_mov_b32_e32 v2, v182
	v_mov_b32_e32 v3, v183
	v_mov_b32_e32 v4, v184
	v_mov_b32_e32 v5, v185
	v_mov_b32_e32 v88, v186
	v_mov_b32_e32 v89, v187
	v_mov_b32_e32 v90, v188
	v_mov_b32_e32 v91, v189
	v_pk_fma_f32 v[2:3], v[32:33], v[2:3], v[88:89]
	v_pk_fma_f32 v[4:5], v[28:29], v[4:5], v[90:91]
	v_cvt_pk_bf16_f32 v28, v2, v3
	s_nop 0
	v_cvt_pk_bf16_f32 v29, v4, v5
	global_store_dwordx2 v[14:15], v[28:29], off offset:512 nt
	s_and_saveexec_b64 s[0:1], vcc
	s_cbranch_execz .LBB0_2259
	v_lshl_add_u64 v[28:29], v[8:9], 0, v[40:41]
	global_store_dwordx4 v[28:29], v[2:5], off offset:1024
.LBB0_2259:
	s_or_b64 exec, exec, s[0:1]
	v_mov_b32_e32 v75, v41
	v_lshl_add_u64 v[28:29], v[16:17], 0, v[74:75]
	v_lshl_add_u64 v[28:29], v[12:13], 0, v[74:75]
	v_pk_mul_f32 v[26:27], v[98:99], v[26:27]
	s_waitcnt vmcnt(7)
	v_mov_b32_e32 v88, v246
	v_mov_b32_e32 v89, v247
	v_mov_b32_e32 v90, v248
	v_mov_b32_e32 v91, v249
	v_mov_b32_e32 v104, v250
	v_mov_b32_e32 v105, v251
	v_mov_b32_e32 v106, v252
	v_mov_b32_e32 v107, v253
	global_load_dwordx4 v[246:249], v40, s[72:73]
	global_load_dwordx4 v[250:253], v40, s[74:75]
	v_pk_add_f32 v[32:33], v[88:89], 1.0 op_sel_hi:[1,0]
	v_pk_add_f32 v[28:29], v[90:91], 1.0 op_sel_hi:[1,0]
	v_pk_fma_f32 v[2:3], v[2:3], v[32:33], v[104:105]
	v_pk_fma_f32 v[4:5], v[4:5], v[28:29], v[106:107]
	v_cvt_pk_bf16_f32 v2, v2, v3
	v_pk_mul_f32 v[28:29], v[102:103], v[10:11]
	v_cvt_pk_bf16_f32 v3, v4, v5
	global_store_dwordx2 v[18:19], v[2:3], off offset:512
	s_nop 0
	v_mov_b32_e32 v2, v190
	v_mov_b32_e32 v3, v191
	v_mov_b32_e32 v4, v192
	v_mov_b32_e32 v5, v193
	v_mov_b32_e32 v88, v194
	v_mov_b32_e32 v89, v195
	v_mov_b32_e32 v90, v196
	v_mov_b32_e32 v91, v197
	v_pk_fma_f32 v[4:5], v[26:27], v[4:5], v[90:91]
	v_pk_fma_f32 v[2:3], v[28:29], v[2:3], v[88:89]
	s_nop 0
	v_cvt_pk_bf16_f32 v26, v2, v3
	v_cvt_pk_bf16_f32 v27, v4, v5
	global_store_dwordx2 v[14:15], v[26:27], off offset:1024 nt
	s_and_saveexec_b64 s[0:1], vcc
	s_cbranch_execz .LBB0_2261
	v_lshl_add_u64 v[26:27], v[8:9], 0, v[40:41]
	global_store_dwordx4 v[26:27], v[2:5], off offset:2048
.LBB0_2261:
	s_or_b64 exec, exec, s[0:1]
	v_mov_b32_e32 v77, v41
	v_lshl_add_u64 v[26:27], v[16:17], 0, v[76:77]
	v_lshl_add_u64 v[32:33], v[12:13], 0, v[76:77]
	s_waitcnt vmcnt(9)
	v_mov_b32_e32 v26, v158
	v_mov_b32_e32 v27, v159
	v_mov_b32_e32 v28, v160
	v_mov_b32_e32 v29, v161
	v_mov_b32_e32 v88, v162
	v_mov_b32_e32 v89, v163
	v_mov_b32_e32 v90, v164
	v_mov_b32_e32 v91, v165
	global_load_dwordx4 v[158:161], v40, s[72:73] offset:1024
	global_load_dwordx4 v[162:165], v40, s[74:75] offset:1024
	v_pk_add_f32 v[26:27], v[26:27], 1.0 op_sel_hi:[1,0]
	v_pk_add_f32 v[28:29], v[28:29], 1.0 op_sel_hi:[1,0]
	v_pk_fma_f32 v[2:3], v[2:3], v[26:27], v[88:89]
	v_pk_fma_f32 v[4:5], v[4:5], v[28:29], v[90:91]
	v_cvt_pk_bf16_f32 v2, v2, v3
	v_mov_b32_e32 v26, v10
	v_cvt_pk_bf16_f32 v3, v4, v5
	global_store_dwordx2 v[18:19], v[2:3], off offset:1024
	s_nop 0
	v_mov_b32_e32 v27, v10
	v_pk_mul_f32 v[28:29], v[114:115], v[10:11]
	v_pk_mul_f32 v[32:33], v[112:113], v[26:27]
	v_mov_b32_e32 v2, v198
	v_mov_b32_e32 v3, v199
	v_mov_b32_e32 v4, v200
	v_mov_b32_e32 v5, v201
	v_mov_b32_e32 v88, v202
	v_mov_b32_e32 v89, v203
	v_mov_b32_e32 v90, v204
	v_mov_b32_e32 v91, v205
	v_pk_fma_f32 v[2:3], v[28:29], v[2:3], v[88:89]
	v_pk_fma_f32 v[4:5], v[32:33], v[4:5], v[90:91]
	v_cvt_pk_bf16_f32 v28, v2, v3
	s_nop 0
	v_cvt_pk_bf16_f32 v29, v4, v5
	global_store_dwordx2 v[14:15], v[28:29], off offset:1536 nt
	s_and_saveexec_b64 s[0:1], vcc
	s_cbranch_execz .LBB0_2263
	v_lshl_add_u64 v[28:29], v[8:9], 0, v[40:41]
	global_store_dwordx4 v[28:29], v[2:5], off offset:3072
.LBB0_2263:
	s_or_b64 exec, exec, s[0:1]
	v_mov_b32_e32 v87, v41
	v_lshl_add_u64 v[28:29], v[16:17], 0, v[86:87]
	v_lshl_add_u64 v[28:29], v[12:13], 0, v[86:87]
	v_pk_mul_f32 v[26:27], v[96:97], v[26:27]
	s_waitcnt vmcnt(10)
	v_mov_b32_e32 v88, v238
	v_mov_b32_e32 v89, v239
	v_mov_b32_e32 v90, v240
	v_mov_b32_e32 v91, v241
	v_mov_b32_e32 v102, v242
	v_mov_b32_e32 v103, v243
	v_mov_b32_e32 v104, v244
	v_mov_b32_e32 v105, v245
	global_load_dwordx4 v[238:241], v40, s[72:73] offset:2048
	global_load_dwordx4 v[242:245], v40, s[74:75] offset:2048
	v_pk_add_f32 v[32:33], v[88:89], 1.0 op_sel_hi:[1,0]
	v_pk_add_f32 v[28:29], v[90:91], 1.0 op_sel_hi:[1,0]
	v_pk_fma_f32 v[2:3], v[2:3], v[32:33], v[102:103]
	v_pk_fma_f32 v[4:5], v[4:5], v[28:29], v[104:105]
	v_cvt_pk_bf16_f32 v2, v2, v3
	v_pk_mul_f32 v[28:29], v[100:101], v[10:11]
	v_cvt_pk_bf16_f32 v3, v4, v5
	global_store_dwordx2 v[18:19], v[2:3], off offset:1536
	s_nop 0
	v_mov_b32_e32 v2, v206
	v_mov_b32_e32 v3, v207
	v_mov_b32_e32 v4, v208
	v_mov_b32_e32 v5, v209
	v_mov_b32_e32 v86, v210
	v_mov_b32_e32 v87, v211
	v_mov_b32_e32 v88, v212
	v_mov_b32_e32 v89, v213
	v_pk_fma_f32 v[4:5], v[26:27], v[4:5], v[88:89]
	v_pk_fma_f32 v[2:3], v[28:29], v[2:3], v[86:87]
	s_nop 0
	v_cvt_pk_bf16_f32 v26, v2, v3
	v_cvt_pk_bf16_f32 v27, v4, v5
	global_store_dwordx2 v[14:15], v[26:27], off offset:2048 nt
	s_and_saveexec_b64 s[0:1], vcc
	s_cbranch_execz .LBB0_2265
	v_mov_b32_e32 v85, v41
	v_lshl_add_u64 v[26:27], v[8:9], 0, v[84:85]
	global_store_dwordx4 v[26:27], v[2:5], off
.LBB0_2265:
	s_or_b64 exec, exec, s[0:1]
	v_mov_b32_e32 v85, v41
	v_lshl_add_u64 v[26:27], v[16:17], 0, v[84:85]
	v_lshl_add_u64 v[32:33], v[12:13], 0, v[84:85]
	s_waitcnt vmcnt(10)
	v_mov_b32_e32 v26, v246
	v_mov_b32_e32 v27, v247
	v_mov_b32_e32 v28, v248
	v_mov_b32_e32 v29, v249
	v_mov_b32_e32 v84, v250
	v_mov_b32_e32 v85, v251
	v_mov_b32_e32 v86, v252
	v_mov_b32_e32 v87, v253
	global_load_dwordx4 v[246:249], v40, s[72:73] offset:3072
	global_load_dwordx4 v[250:253], v40, s[74:75] offset:3072
	v_pk_add_f32 v[26:27], v[26:27], 1.0 op_sel_hi:[1,0]
	v_pk_add_f32 v[28:29], v[28:29], 1.0 op_sel_hi:[1,0]
	v_pk_fma_f32 v[2:3], v[2:3], v[26:27], v[84:85]
	v_pk_fma_f32 v[4:5], v[4:5], v[28:29], v[86:87]
	v_cvt_pk_bf16_f32 v2, v2, v3
	v_mov_b32_e32 v26, v10
	v_cvt_pk_bf16_f32 v3, v4, v5
	global_store_dwordx2 v[18:19], v[2:3], off offset:2048
	s_nop 0
	v_mov_b32_e32 v27, v10
	v_pk_mul_f32 v[28:29], v[94:95], v[10:11]
	v_pk_mul_f32 v[24:25], v[24:25], v[26:27]
	v_mov_b32_e32 v2, v214
	v_mov_b32_e32 v3, v215
	v_mov_b32_e32 v4, v216
	v_mov_b32_e32 v5, v217
	v_mov_b32_e32 v84, v218
	v_mov_b32_e32 v85, v219
	v_mov_b32_e32 v86, v220
	v_mov_b32_e32 v87, v221
	v_pk_fma_f32 v[2:3], v[28:29], v[2:3], v[84:85]
	v_pk_fma_f32 v[4:5], v[24:25], v[4:5], v[86:87]
	v_cvt_pk_bf16_f32 v24, v2, v3
	s_nop 0
	v_cvt_pk_bf16_f32 v25, v4, v5
	global_store_dwordx2 v[14:15], v[24:25], off offset:2560 nt
	s_and_saveexec_b64 s[0:1], vcc
	s_cbranch_execz .LBB0_2267
	v_mov_b32_e32 v83, v41
	v_lshl_add_u64 v[24:25], v[8:9], 0, v[82:83]
	global_store_dwordx4 v[24:25], v[2:5], off
